# deferred-max threshold THR 8->32 nats in forgetting attention (fewer accumulator rescales; same online-softmax math); on top of v14
# baseline (speedup 1.0000x reference)
; #define LAS __attribute__((address_space(3)))
; __device__ __forceinline__ unsigned xb_ld(unsigned* p)              { return __hip_atomic_load(p, __ATOMIC_RELAXED, __HIP_MEMORY_SCOPE_AGENT); }
; __device__ __forceinline__ void xcd_barrier_complete(unsigned* bar, unsigned x, unsigned& nloc, unsigned& nx) {
;     const unsigned G = gridDim.x * gridDim.y * gridDim.z;
;     unsigned sum, cnt, mine, sp = 0u;
;     for (;;) {
;         sum = 0u; cnt = 0u; mine = 0u;
; #pragma unroll
;         for (unsigned j = 0; j < 16; ++j) { const unsigned c = xb_ld(&bar[XB_XCNT(j)]); sum += c; cnt += (c > 0u) ? 1u : 0u; mine = (j == x) ? c : mine; }
; __global__ void __launch_bounds__(NTHR, 2) fwd_megakernel(Args args) {
;     ...
;     unsigned char* ws = args.ws;
;     float* rn2 = (float*)(ws + WS_RN2);
;     float* logf = (float*)(ws + WS_LOGF); float* cs = (float*)(ws + WS_CS);
;     bf16* Win_t = (bf16*)(ws + WS_WIN); bf16* Wc_t = (bf16*)(ws + WS_WC); bf16* Wa_t = (bf16*)(ws + WS_WA); bf16* Wmix_t = (bf16*)(ws + WS_WMIX);
;     bf16* W1_t = (bf16*)(ws + WS_W1); bf16* W2_t = (bf16*)(ws + WS_W2);
;     bf16* Z = (bf16*)(ws + WS_Z); bf16* XN = (bf16*)(ws + WS_XN); bf16* CONVY = (bf16*)(ws + WS_CONVY); bf16* ATTO = (bf16*)(ws + WS_ATTO);
;     bf16* XG = (bf16*)(ws + WS_Z + 256 * MiB);
;     float* rowss = (float*)(ws + WS_RSS);
;     float* xres = args.out;
;     volatile LAS unsigned* bst = (volatile LAS unsigned*)(L + att::LDS_BYTES + 65536 + 64);
;     if (tid0 < 2) bst[tid0] = 0u;
;     __syncthreads();
;     const XcdBarrier xbar = xcd_barrier_post((unsigned*)(ws + WS_BAR), bst);
.LBB0_5:
	s_or_b64 exec, exec, s[0:1]
	s_lshr_b32 s97, s6, 6
	s_lshl_b32 s0, s2, 3
	s_add_i32 s24, s97, s0
	s_lshl_b32 s80, s70, 3
	s_add_u32 s88, s68, 0x24000000
	s_addc_u32 s89, s69, 0
	s_add_u32 s18, s68, 0x100000
	s_addc_u32 s19, s69, 0
	s_add_u32 s20, s68, 0x180000
	s_addc_u32 s21, s69, 0
	s_add_u32 s26, s68, 0x200000
	s_addc_u32 s27, s69, 0
	s_add_u32 s28, s68, 0x2a00000
	s_addc_u32 s29, s69, 0
	s_add_u32 s30, s68, 0x2e00000
	s_addc_u32 s31, s69, 0
	s_add_u32 s34, s68, 0x3200000
	s_addc_u32 s35, s69, 0
	s_add_u32 s36, s68, 0x3a00000
	s_addc_u32 s37, s69, 0
	s_add_u32 s38, s68, 0x5a00000
	s_addc_u32 s39, s69, 0
	s_add_u32 s4, s68, 0x8000000
	s_addc_u32 s5, s69, 0
	s_add_u32 s6, s68, 0x1c000000
	s_addc_u32 s7, s69, 0
	s_add_u32 s8, s68, 0x20000000
	s_addc_u32 s9, s69, 0
	s_add_u32 s42, s68, 0x22000000
	s_addc_u32 s43, s69, 0
	s_add_u32 s10, s68, 0x18000000
	s_addc_u32 s11, s69, 0
	s_add_u32 s12, s68, 0x20000
	s_addc_u32 s13, s69, 0
	s_cmpk_lt_i32 s2, 0x100
	s_cselect_b64 s[0:1], -1, 0
	v_writelane_b32 v252, s0, 26
	v_lshrrev_b32_e32 v1, 20, v0
	v_lshrrev_b32_e32 v0, 10, v0
	v_writelane_b32 v252, s1, 27
	s_lshl_b32 s0, s97, 14
	s_add_i32 s0, s0, 0
	s_cmpk_lt_i32 s24, 0x7800
	v_writelane_b32 v252, s0, 28
	s_cselect_b64 s[0:1], -1, 0
	v_writelane_b32 v252, s0, 29
	s_ashr_i32 s25, s24, 31
	v_or_b32_e32 v0, v0, v1
	v_writelane_b32 v252, s1, 30
	s_lshl_b64 s[0:1], s[24:25], 13
	v_writelane_b32 v252, s0, 31
	s_cmpk_lt_i32 s24, 0x4000
	s_mul_i32 s71, s71, s70
	v_writelane_b32 v252, s1, 32
	s_cselect_b64 s[0:1], -1, 0
	v_writelane_b32 v252, s0, 33
	s_mul_i32 s71, s71, s16
	v_mbcnt_lo_u32_b32 v1, -1, 0
	v_writelane_b32 v252, s1, 34
	s_add_u32 s0, s68, 0x4200
	s_addc_u32 s1, s69, 0
	v_writelane_b32 v252, s0, 35
	v_mov_b32_e32 v193, 0
	v_mov_b32_e32 v237, 0x358637bd
	v_writelane_b32 v252, s1, 36
	s_add_u32 s0, s68, 0x4400
	s_addc_u32 s1, s69, 0
	v_writelane_b32 v252, s0, 37
	v_mov_b32_e32 v206, 0x260
	v_mbcnt_hi_u32_b32 v203, -1, v1
	v_writelane_b32 v252, s1, 38
	s_add_u32 s0, s68, 0x4500
	s_addc_u32 s1, s69, 0
	v_writelane_b32 v252, s0, 39
	v_mov_b32_e32 v207, 0xff800000
	v_mov_b32_e32 v208, 0x5000
	v_writelane_b32 v252, s1, 40
	s_add_u32 s0, s68, 0x4600
	s_addc_u32 s1, s69, 0
	v_writelane_b32 v252, s0, 41
	v_mov_b64_e32 v[232:233], 0x200
	v_mov_b64_e32 v[204:205], 0x1ff
	v_writelane_b32 v252, s1, 42
	s_add_u32 s0, s68, 0x4700
	s_addc_u32 s1, s69, 0
	v_writelane_b32 v252, s0, 43
	v_mov_b64_e32 v[250:251], 0x7ff
	s_movk_i32 s61, 0x4000
	v_writelane_b32 v252, s1, 44
	s_add_u32 s0, s68, 0x4800
	s_addc_u32 s1, s69, 0
	v_writelane_b32 v252, s0, 45
	s_movk_i32 s81, 0x7fff
	s_mov_b32 s96, 0xffff0000
	v_writelane_b32 v252, s1, 46
	s_add_u32 s0, s68, 0x4900
	s_addc_u32 s1, s69, 0
	v_writelane_b32 v252, s0, 47
	s_movk_i32 s84, 0x1000
	s_movk_i32 s85, 0x5000
	v_writelane_b32 v252, s1, 48
	s_add_u32 s0, s68, 0x4a00
	s_addc_u32 s1, s69, 0
	v_writelane_b32 v252, s0, 49
	s_mov_b32 s90, 0x42000000
	s_mov_b32 s60, 0x3e0293ee
	v_writelane_b32 v252, s1, 50
	s_add_u32 s0, s68, 0x4b00
	s_addc_u32 s1, s69, 0
	v_writelane_b32 v252, s0, 51
	s_nop 1
	v_writelane_b32 v252, s1, 52
	s_add_u32 s0, s68, 0x4c00
	s_addc_u32 s1, s69, 0
	v_writelane_b32 v252, s0, 53
	s_nop 1
	v_writelane_b32 v252, s1, 54
	s_add_u32 s0, s68, 0x4d00
	s_addc_u32 s1, s69, 0
	s_add_u32 s82, s68, 0x4e00
	v_writelane_b32 v252, s0, 55
	s_addc_u32 s83, s69, 0
	s_nop 0
	v_writelane_b32 v252, s1, 56
	s_add_u32 s0, s68, 0x4f00
	s_addc_u32 s1, s69, 0
	s_add_u32 s72, s68, 0x5000
	s_addc_u32 s73, s69, 0
	s_add_u32 s74, s68, 0x5100
	s_addc_u32 s75, s69, 0
	s_add_u32 s76, s68, 0x5200
	s_addc_u32 s77, s69, 0
	s_add_u32 s78, s68, 0x5300
	s_addc_u32 s79, s69, 0
	s_cmp_eq_u32 s3, 15
	s_cselect_b64 s[22:23], -1, 0
	v_writelane_b32 v252, s22, 57
	s_cmp_eq_u32 s3, 14
	s_nop 0
	v_writelane_b32 v252, s23, 58
	s_cselect_b64 s[22:23], -1, 0
	v_writelane_b32 v252, s22, 59
	s_cmp_eq_u32 s3, 13
	s_nop 0
	v_writelane_b32 v252, s23, 60
	s_cselect_b64 s[22:23], -1, 0
	v_writelane_b32 v252, s22, 61
	s_cmp_eq_u32 s3, 12
	s_nop 0
	v_writelane_b32 v252, s23, 62
	s_cselect_b64 s[22:23], -1, 0
	v_writelane_b32 v252, s22, 63
	s_cmp_eq_u32 s3, 11
	s_nop 0
	v_writelane_b32 v253, s23, 0
	s_cselect_b64 s[22:23], -1, 0
	v_writelane_b32 v253, s22, 1
	s_cmp_eq_u32 s3, 10
	s_nop 0
	v_writelane_b32 v253, s23, 2
	s_cselect_b64 s[22:23], -1, 0
	v_writelane_b32 v253, s22, 3
	s_cmp_eq_u32 s3, 9
	s_nop 0
	v_writelane_b32 v253, s23, 4
	s_cselect_b64 s[22:23], -1, 0
	v_writelane_b32 v253, s22, 5
	s_cmp_eq_u32 s3, 8
	s_nop 0
	v_writelane_b32 v253, s23, 6
	s_cselect_b64 s[22:23], -1, 0
	v_writelane_b32 v253, s22, 7
	s_cmp_eq_u32 s3, 7
	s_nop 0
	v_writelane_b32 v253, s23, 8
	s_cselect_b64 s[22:23], -1, 0
	v_writelane_b32 v253, s22, 9
	s_cmp_eq_u32 s3, 6
	s_nop 0
	v_writelane_b32 v253, s23, 10
	s_cselect_b64 s[22:23], -1, 0
	v_writelane_b32 v253, s22, 11
	s_cmp_eq_u32 s3, 5
	s_nop 0
	v_writelane_b32 v253, s23, 12
	s_cselect_b64 s[22:23], -1, 0
	v_writelane_b32 v253, s22, 13
	s_cmp_eq_u32 s3, 4
	s_nop 0
	v_writelane_b32 v253, s23, 14
	s_cselect_b64 s[22:23], -1, 0
	v_writelane_b32 v253, s22, 15
	s_cmp_eq_u32 s3, 3
	s_nop 0
	v_writelane_b32 v253, s23, 16
	s_cselect_b64 s[22:23], -1, 0
	v_writelane_b32 v253, s22, 17
	s_cmp_eq_u32 s3, 2
	s_nop 0
	v_writelane_b32 v253, s23, 18
	s_cselect_b64 s[22:23], -1, 0
	v_writelane_b32 v253, s22, 19
	s_cmp_eq_u32 s3, 1
	s_nop 0
	v_writelane_b32 v253, s23, 20
	s_cselect_b64 s[22:23], -1, 0
	v_writelane_b32 v253, s22, 21
	s_cmp_eq_u32 s3, 0
	s_nop 0
	v_writelane_b32 v253, s23, 22
	s_cselect_b64 s[22:23], -1, 0
	s_lshl_b32 s3, s17, 2
	s_add_u32 s3, s14, s3
	v_writelane_b32 v253, s22, 23
	s_addc_u32 s14, s15, 0
	s_nop 0
;     __host__ __device__ bool next(int i, Unit& u) const {
;         const long L = (long)i * G + c; if (L >= nwg) return false;
;         int wgid = (int)L; { const int q = nwg / NXCD, r = nwg % NXCD, xcd = wgid % NXCD, off = wgid / NXCD; wgid = (xcd < r ? xcd * (q + 1) : r * (q + 1) + (xcd - r) * q) + off; }
;         const int nig = WGM * nN, gid = wgid / nig, fm = gid * WGM, gsz = (nM - fm) < WGM ? (nM - fm) : WGM;
;         u.pm = fm + ((wgid % nig) % gsz); u.pn = (wgid % nig) / gsz; return true;
; template <class Epi, class Sched, bool ALIGN_EPI = false, bool SP2 = false>
; __device__ __forceinline__ void gemm_phase(PG8_LAS unsigned char* lds, const Gemm g, const Sched& S, const Epi& E) {
;     ...
;     const char* cA = (const char*)g.A + (size_t)cur.pm * tstepA; const char* cB = (const char*)g.Bt + (size_t)cur.pn * tstepB;
	v_writelane_b32 v253, s23, 24
	s_add_u32 s22, s3, 0x1400
	s_addc_u32 s23, s14, 0
	v_writelane_b32 v253, s22, 25
	s_nop 1
	v_writelane_b32 v253, s23, 26
	s_add_u32 s22, s3, 0x2400
	s_addc_u32 s23, s14, 0
	v_writelane_b32 v253, s22, 27
	s_add_u32 s14, s68, 0x7400
	s_addc_u32 s15, s69, 0
	v_writelane_b32 v253, s23, 28
	v_writelane_b32 v253, s14, 29
	s_nop 1
	v_writelane_b32 v253, s15, 30
	s_add_u32 s14, s68, 0x7500
	s_addc_u32 s15, s69, 0
	v_writelane_b32 v253, s14, 31
	s_cmp_lt_i32 s2, 8
	s_nop 0
	v_writelane_b32 v253, s15, 32
	s_cselect_b64 s[14:15], -1, 0
	v_writelane_b32 v253, s14, 33
	s_ashr_i32 s3, s2, 31
	s_nop 0
	v_writelane_b32 v253, s15, 34
	s_lshl_b64 s[14:15], s[2:3], 2
	s_add_u32 s14, s18, s14
	v_writelane_b32 v253, s18, 35
	s_addc_u32 s15, s19, s15
	s_nop 0
	v_writelane_b32 v253, s19, 36
	v_writelane_b32 v253, s14, 37
	s_nop 1
	v_writelane_b32 v253, s15, 38
	s_lshl_b64 s[14:15], s[2:3], 16
	v_writelane_b32 v253, s20, 39
	s_add_u32 s14, s20, s14
	v_writelane_b32 v253, s21, 40
	s_addc_u32 s15, s21, s15
	v_writelane_b32 v253, s14, 41
	s_cmpk_lt_i32 s2, 0xa00
	s_nop 0
	v_writelane_b32 v253, s15, 42
	s_cselect_b64 s[14:15], -1, 0
	v_writelane_b32 v253, s14, 43
	s_ashr_i32 s33, s70, 31
	s_nop 0
	v_writelane_b32 v253, s15, 44
	s_lshr_b32 s14, s3, 29
	s_add_i32 s14, s2, s14
	s_ashr_i32 s15, s14, 3
	s_and_b32 s14, s14, -8
	s_sub_i32 s14, s2, s14
	s_add_u32 s17, s68, 0x8001800
	v_writelane_b32 v253, s17, 45
	s_addc_u32 s17, s69, 0
	v_writelane_b32 v253, s17, 46
	s_add_u32 s17, s68, 0x8002000
	v_writelane_b32 v253, s17, 47
	s_addc_u32 s17, s69, 0
	v_writelane_b32 v253, s17, 48
	s_add_u32 s17, s68, 0x8000
	v_writelane_b32 v253, s17, 49
	s_addc_u32 s17, s69, 0
	v_writelane_b32 v253, s17, 50
	s_ashr_i32 s17, s70, 3
	s_mul_i32 s17, s17, s14
	s_add_i32 s17, s17, s15
	s_and_b32 s18, s70, 7
	s_add_u32 s20, s68, 0x8003000
	s_addc_u32 s21, s69, 0
	v_writelane_b32 v253, s20, 51
	s_cmpk_lt_i32 s2, 0x200
	s_nop 0
	v_writelane_b32 v253, s21, 52
	s_cselect_b64 s[20:21], -1, 0
	v_writelane_b32 v253, s20, 53
	s_lshl_b32 s19, s14, 6
	s_nop 0
	v_writelane_b32 v253, s21, 54
	s_add_u32 s20, s68, 0x8004000
	s_addc_u32 s21, s69, 0
	v_writelane_b32 v253, s20, 55
	s_cmpk_lt_i32 s2, 0x800
	s_nop 0
	v_writelane_b32 v253, s21, 56
	s_cselect_b64 s[20:21], -1, 0
	v_writelane_b32 v253, s20, 57
	s_nop 1
	v_writelane_b32 v253, s21, 58
	s_lshl_b32 s20, s14, 8
	s_cmp_lt_i32 s14, 0
	s_mul_i32 s21, s14, 0x41
	s_cselect_b32 s19, s21, s19
	s_movk_i32 s21, 0x141
	s_cselect_b32 s21, s21, 0x140
	s_mul_i32 s21, s14, s21
	s_mulk_i32 s14, 0x101
	s_cselect_b32 s22, s14, s20
	s_add_i32 s21, s21, s15
	s_mul_hi_i32 s14, s21, 0x66666667
	s_lshr_b32 s20, s14, 31
	s_ashr_i32 s14, s14, 5
	s_add_i32 s14, s14, s20
	s_mul_i32 s20, s14, 0x50
	s_sub_i32 s20, s21, s20
	s_bfe_u32 s21, s20, 0x10007
	s_add_i32 s21, s20, s21
	s_and_b32 s23, s21, 0xfe
	s_sub_i32 s20, s20, s23
	s_bfe_i32 s21, s21, 0x80000
	s_lshl_b32 s14, s14, 1
	s_sext_i32_i16 s21, s21
	s_sext_i32_i8 s20, s20
	s_add_i32 s44, s14, s20
	s_ashr_i32 s14, s21, 1
	v_writelane_b32 v253, s14, 59
	s_lshr_b32 s14, s21, 1
	s_add_u32 s20, s68, 0x18fffc
	s_addc_u32 s21, s69, 0
	v_writelane_b32 v253, s20, 60
	s_nop 1
	v_writelane_b32 v253, s21, 61
	s_add_u32 s20, s68, 0x19fffc
	s_addc_u32 s21, s69, 0
	v_writelane_b32 v253, s20, 62
	s_nop 1
	v_writelane_b32 v253, s21, 63
	s_add_u32 s20, s68, 0x1afffc
	s_addc_u32 s21, s69, 0
	v_writelane_b32 v254, s20, 0
	s_nop 1
	v_writelane_b32 v254, s21, 1
	s_add_u32 s20, s68, 0x1bfffc
	s_addc_u32 s21, s69, 0
	v_writelane_b32 v254, s20, 2
	s_nop 1
	v_writelane_b32 v254, s21, 3
	s_add_u32 s20, s68, 0x1cfffc
	s_addc_u32 s21, s69, 0
	v_writelane_b32 v254, s20, 4
	s_nop 1
	v_writelane_b32 v254, s21, 5
	s_add_u32 s20, s68, 0x1dfffc
	s_addc_u32 s21, s69, 0
	v_writelane_b32 v254, s20, 6
	s_nop 1
	v_writelane_b32 v254, s21, 7
	s_add_u32 s20, s68, 0x1efffc
	s_addc_u32 s21, s69, 0
	v_writelane_b32 v254, s20, 8
	s_nop 1
	v_writelane_b32 v254, s21, 9
	s_add_u32 s20, s68, 0x1ffffc
	s_addc_u32 s21, s69, 0
	v_writelane_b32 v254, s20, 10
	s_cmp_eq_u32 s18, 0
	s_cselect_b32 s17, s17, s2
	v_writelane_b32 v254, s21, 11
	v_writelane_b32 v254, s17, 12
	s_add_i32 s17, s19, s15
	s_ashr_i32 s18, s17, 31
	s_lshr_b32 s18, s18, 28
	s_add_i32 s18, s17, s18
	s_and_b32 s19, s18, 0xfff0
	s_sub_i32 s17, s17, s19
	s_bfe_u32 s19, s17, 0x10007
	s_add_i32 s19, s17, s19
	s_and_b32 s20, s19, 0xfe
	s_sub_i32 s17, s17, s20
	s_ashr_i32 s18, s18, 4
	s_bfe_i32 s19, s19, 0x80000
	s_lshl_b32 s18, s18, 1
	s_sext_i32_i16 s19, s19
	s_sext_i32_i8 s17, s17
	s_add_i32 s46, s18, s17
	s_lshr_b32 s18, s19, 1
	s_ashr_i32 s47, s46, 31
	s_bfe_i64 s[40:41], s[18:19], 0x100000
	s_ashr_i32 s17, s19, 1
	s_lshl_b64 s[18:19], s[46:47], 19
	s_lshl_b64 s[20:21], s[40:41], 19
	v_writelane_b32 v254, s17, 13
	s_add_u32 s48, s28, s20
	v_writelane_b32 v254, s28, 14
	s_addc_u32 s49, s29, s21
	s_mov_b64 s[68:69], 0x80
	v_writelane_b32 v254, s29, 15
	s_add_u32 s28, s48, 0x40000
	s_addc_u32 s29, s49, 0
	v_writelane_b32 v254, s28, 16
	s_nop 1
	v_writelane_b32 v254, s29, 17
	s_add_u32 s28, s8, s18
	s_addc_u32 s29, s9, s19
	s_add_u32 s50, s28, 0x40000
	v_writelane_b32 v254, s28, 18
	s_addc_u32 s51, s29, 0
	s_nop 0
	v_writelane_b32 v254, s29, 19
	v_writelane_b32 v254, s50, 20
	s_add_u32 s28, s48, 0x40080
	s_nop 0
	v_writelane_b32 v254, s51, 21
	v_writelane_b32 v254, s48, 22
	s_addc_u32 s29, s49, 0
	s_add_u32 s20, s30, s20
	v_writelane_b32 v254, s49, 23
	v_writelane_b32 v254, s28, 24
	s_nop 1
	v_writelane_b32 v254, s29, 25
	v_writelane_b32 v254, s30, 26
	s_addc_u32 s21, s31, s21
	s_add_u32 s28, s20, 0x40000
	v_writelane_b32 v254, s31, 27
	s_addc_u32 s29, s21, 0
	v_writelane_b32 v254, s28, 28
; #define PG8_STAGE(bufoff, gbase, voff) do { _Pragma("unroll") for (int _i = 0; _i < 2; ++_i) _Pragma("unroll") for (int _r = 0; _r < PG8_NREP; ++_r) \
;         __builtin_amdgcn_global_load_lds((const unsigned*)((const char*)(gbase) + (voff)[_i]), (PG8_LAS unsigned*)(lds + (bufoff) + ldsw + _i * 8192), 16, 0, 0); } while (0)
; #define PG8_WAIT_V(n) do { if ((n) == 0) asm volatile("s_waitcnt vmcnt(0)" ::: "memory"); else if ((n) == 2) asm volatile("s_waitcnt vmcnt(4)" ::: "memory"); else if ((n) == 4) asm volatile("s_waitcnt vmcnt(8)" ::: "memory"); \
;     else if ((n) == 6) asm volatile("s_waitcnt vmcnt(12)" ::: "memory"); else asm volatile("s_waitcnt vmcnt(16)" ::: "memory"); } while (0)
; #define PG8_WAIT_V(n) asm volatile("s_waitcnt vmcnt(" #n ")" ::: "memory")
; #define PG8_BAR __builtin_amdgcn_s_barrier()
; template <class Epi, class Sched, bool ALIGN_EPI = false, bool SP2 = false>
; __device__ __forceinline__ void gemm_phase(PG8_LAS unsigned char* lds, const Gemm g, const Sched& S, const Epi& E) {
;     ...
;     const size_t hstepA = (size_t)HALF * lda * 2, hstepB = (size_t)HALF * K * 2;
;     const size_t tstepA = 2 * hstepA, tstepB = 2 * hstepB;
;     ...
;     const char* cA = (const char*)g.A + (size_t)cur.pm * tstepA; const char* cB = (const char*)g.Bt + (size_t)cur.pn * tstepB;
;     S.a_ready(cur);
;     if constexpr (SP2) {
;         PG8_STAGE(PG8_SB(0, 0), cB, voffB); PG8_STAGE(PG8_SB(0, 1), cB + hstepB, voffB); PG8_STAGE(PG8_SA(0, 0), cA, voffA); PG8_STAGE(PG8_SA(0, 1), cA + hstepA, voffA);
;         if (wr == 1) PG8_BAR;
;         PG8_WAIT_V(2); PG8_BAR;
;         PG8_STAGE(PG8_SB(1, 0), cB + kstep, voffB); PG8_STAGE(PG8_SA(1, 0), cA + kstep, voffA); PG8_STAGE(PG8_SB(1, 1), cB + hstepB + kstep, voffB);
;         PG8_WAIT_V(6); PG8_BAR;
;     } else {
;         PG8_STAGE(PG8_SB(0, 0), cB, voffB); PG8_STAGE(PG8_SA(0, 0), cA, voffA); PG8_STAGE(PG8_SB(0, 1), cB + hstepB, voffB); PG8_STAGE(PG8_SA(0, 1), cA + hstepA, voffA);
;         if (wr == 1) PG8_BAR;
;         PG8_WAIT_V(4); PG8_BAR;
;         PG8_STAGE(PG8_SB(1, 0), cB + kstep, voffB); PG8_STAGE(PG8_SA(1, 0), cA + kstep, voffA); PG8_STAGE(PG8_SB(1, 1), cB + hstepB + kstep, voffB);
	s_add_u32 s18, s42, s18
	s_addc_u32 s19, s43, s19
	v_writelane_b32 v254, s29, 29
	v_writelane_b32 v254, s42, 30
	v_writelane_b32 v254, s43, 31
	s_add_u32 s28, s18, 0x40000
	v_writelane_b32 v254, s18, 32
	s_addc_u32 s29, s19, 0
	s_nop 0
	v_writelane_b32 v254, s19, 33
	v_writelane_b32 v254, s28, 34
	s_add_u32 s18, s20, 0x40080
	s_nop 0
	v_writelane_b32 v254, s29, 35
	v_writelane_b32 v254, s20, 36
	s_addc_u32 s19, s21, 0
	s_add_i32 s15, s22, s15
	s_ashr_i32 s17, s15, 31
	v_writelane_b32 v254, s21, 37
	s_lshr_b32 s17, s17, 26
	v_writelane_b32 v254, s18, 38
	s_add_i32 s17, s15, s17
	s_mov_b32 s28, s87
	v_writelane_b32 v254, s19, 39
	s_and_b32 s18, s17, 0xffc0
	s_sub_i32 s15, s15, s18
	s_bfe_u32 s18, s15, 0x10007
	s_add_i32 s18, s15, s18
	s_and_b32 s19, s18, 0xfe
	s_sub_i32 s15, s15, s19
	s_ashr_i32 s17, s17, 6
	s_bfe_i32 s18, s18, 0x80000
	s_lshl_b32 s17, s17, 1
	s_sext_i32_i16 s18, s18
	s_sext_i32_i8 s15, s15
	s_add_i32 s22, s17, s15
	s_ashr_i32 s15, s18, 1
	v_writelane_b32 v254, s15, 40
	s_lshr_b32 s18, s18, 1
	s_mov_b32 s20, s22
	s_ashr_i32 s23, s22, 31
	s_bfe_i64 s[18:19], s[18:19], 0x100000
	v_writelane_b32 v254, s20, 41
	s_lshl_b64 s[18:19], s[18:19], 20
	s_nop 0
	v_writelane_b32 v254, s21, 42
	s_lshl_b64 s[20:21], s[22:23], 20
	s_add_u32 s18, s36, s18
	s_addc_u32 s19, s37, s19
	s_add_u32 s22, s18, 0x80000
	s_addc_u32 s23, s19, 0
	v_writelane_b32 v254, s22, 43
	s_add_u32 s20, s10, s20
	s_addc_u32 s21, s11, s21
	v_writelane_b32 v254, s23, 44
	s_add_u32 s22, s20, 0x80000
	v_writelane_b32 v254, s20, 45
	s_addc_u32 s23, s21, 0
	s_nop 0
	v_writelane_b32 v254, s21, 46
	v_writelane_b32 v254, s22, 47
	s_add_u32 s20, s18, 0x80080
	s_nop 0
	v_writelane_b32 v254, s23, 48
	v_writelane_b32 v254, s18, 49
	s_addc_u32 s21, s19, 0
	s_nop 0
	v_writelane_b32 v254, s19, 50
	v_writelane_b32 v254, s20, 51
	s_lshl_b64 s[18:19], s[46:47], 22
	s_nop 0
	v_writelane_b32 v254, s21, 52
	s_lshl_b64 s[20:21], s[40:41], 22
	s_add_u32 s20, s38, s20
	v_writelane_b32 v254, s38, 53
	s_addc_u32 s21, s39, s21
	s_add_u32 s22, s20, 0x200000
	v_writelane_b32 v254, s39, 54
	s_addc_u32 s23, s21, 0
	v_writelane_b32 v254, s22, 55
	s_add_u32 s18, s4, s18
	s_addc_u32 s19, s5, s19
	v_writelane_b32 v254, s23, 56
	s_add_u32 s22, s18, 0x200000
	v_writelane_b32 v254, s18, 57
	s_addc_u32 s23, s19, 0
	s_movk_i32 s39, 0xbfff
	v_writelane_b32 v254, s19, 58
	v_writelane_b32 v254, s22, 59
	s_add_u32 s18, s20, 0x200080
	s_nop 0
	v_writelane_b32 v254, s23, 60
	v_writelane_b32 v254, s20, 61
	s_addc_u32 s19, s21, 0
	s_ashr_i32 s45, s44, 31
	v_writelane_b32 v254, s21, 62
	v_writelane_b32 v254, s18, 63
	s_bfe_i64 s[14:15], s[14:15], 0x100000
	s_lshl_b64 s[14:15], s[14:15], 20
	v_writelane_b32 v255, s19, 0
	s_mov_b32 s18, s44
	v_writelane_b32 v255, s18, 1
	s_nop 1
	v_writelane_b32 v255, s19, 2
	s_lshl_b64 s[18:19], s[44:45], 20
	s_add_u32 s14, s26, s14
	v_writelane_b32 v255, s26, 3
	s_addc_u32 s15, s27, s15
	s_add_u32 s20, s14, 0x80000
	v_writelane_b32 v255, s27, 4
	s_addc_u32 s21, s15, 0
	v_writelane_b32 v255, s20, 5
	s_add_u32 s18, s6, s18
	s_addc_u32 s19, s7, s19
	v_writelane_b32 v255, s21, 6
	s_add_u32 s20, s18, 0x80000
	v_writelane_b32 v255, s18, 7
	s_addc_u32 s21, s19, 0
	s_nop 0
	v_writelane_b32 v255, s19, 8
	v_writelane_b32 v255, s20, 9
	s_add_u32 s18, s14, 0x80080
	s_nop 0
	v_writelane_b32 v255, s21, 10
	v_writelane_b32 v255, s14, 11
	s_addc_u32 s19, s15, 0
	s_nop 0
	v_writelane_b32 v255, s15, 12
	v_writelane_b32 v255, s18, 13
	s_lshl_b64 s[14:15], s[40:41], 20
	s_nop 0
	v_writelane_b32 v255, s19, 14
	s_mov_b32 s18, s46
	v_writelane_b32 v255, s18, 15
	s_nop 1
	v_writelane_b32 v255, s19, 16
	s_lshl_b64 s[18:19], s[46:47], 20
	s_add_u32 s20, s34, s14
	v_writelane_b32 v255, s34, 17
	s_addc_u32 s21, s35, s15
	s_add_u32 s14, s20, 0x80000
	v_writelane_b32 v255, s35, 18
	s_addc_u32 s15, s21, 0
	v_writelane_b32 v255, s14, 19
	s_add_u32 s18, s6, s18
	s_addc_u32 s19, s7, s19
	v_writelane_b32 v255, s15, 20
	s_movk_i32 s14, 0x3ff
	v_and_or_b32 v0, v0, s14, v202
	s_add_u32 s14, s18, 0x80000
	v_writelane_b32 v255, s18, 21
	s_addc_u32 s15, s19, 0
	s_mov_b64 s[34:35], 0x2000
	v_writelane_b32 v255, s19, 22
	v_writelane_b32 v255, s14, 23
	s_nop 1
	v_writelane_b32 v255, s15, 24
	s_add_u32 s14, s20, 0x80080
	v_writelane_b32 v255, s20, 25
	s_addc_u32 s15, s21, 0
	s_nop 0
	v_writelane_b32 v255, s21, 26
	v_writelane_b32 v255, s14, 27
	s_nop 1
	v_writelane_b32 v255, s15, 28
	s_abs_i32 s14, s70
	s_sub_i32 s15, 1, s14
	s_cmp_lt_u32 s14, 2
	s_cselect_b32 s15, s15, 1
	s_sub_i32 s16, s15, s14
	s_cmp_ge_u32 s15, s14
	s_cselect_b32 s14, s16, s15
	s_cmp_eq_u32 s2, s14
	s_cselect_b64 s[14:15], -1, 0
	v_writelane_b32 v255, s14, 29
	s_lshl_b32 s22, s70, 10
	s_add_i32 s38, 0, 0x20808
	v_writelane_b32 v255, s15, 30
	s_lshl_b32 s14, s2, 8
	s_lshl_b32 s15, s97, 5
	s_add_i32 s14, s14, s15
	v_writelane_b32 v255, s14, 31
	s_lshl_b32 s14, s2, 10
	v_writelane_b32 v255, s14, 32
	s_lshl_b32 s14, s70, 8
	v_writelane_b32 v255, s14, 33
	s_add_i32 s14, s24, 0xa800
	v_writelane_b32 v255, s14, 34
	s_add_i32 s14, s24, 0xc800
	v_writelane_b32 v255, s14, 35
	s_add_i32 s14, s24, 0xd000
	v_writelane_b32 v255, s14, 36
	s_add_i32 s14, s24, 0xd400
	v_writelane_b32 v255, s14, 37
	s_mov_b32 s14, s24
	v_writelane_b32 v255, s14, 38
	s_nop 1
	v_writelane_b32 v255, s15, 39
	s_add_i32 s14, s24, 0xd800
	v_writelane_b32 v255, s14, 40
	s_add_i32 s14, 0, 0x20840
	v_writelane_b32 v255, s14, 41
	s_add_i32 s14, 0, 0x20844
	v_writelane_b32 v255, s14, 42
	s_add_i32 s14, 0, 0x20800
	v_writelane_b32 v255, s14, 43
	s_add_i32 s14, 0, 0x2080c
	v_writelane_b32 v255, s14, 44
	s_add_i32 s14, 0, 0x20804
	v_writelane_b32 v255, s14, 45
	v_cmp_eq_u32_e64 s[14:15], 0, v0
	s_nop 1
	v_writelane_b32 v255, s14, 46
	s_nop 1
	v_writelane_b32 v255, s15, 47
	v_writelane_b32 v255, s56, 48
	s_mov_b64 s[14:15], -1
	s_nop 0
	v_writelane_b32 v255, s57, 49
	v_writelane_b32 v255, s97, 50
	v_writelane_b32 v255, s36, 51
	s_nop 1
	v_writelane_b32 v255, s37, 52
	v_writelane_b32 v255, s22, 53
	s_branch .LBB0_8
